# merge3 plus s_setprio raised around each MFMA group of the shared-A merge K-loop
# speedup vs baseline: 1.1003x; 1.0055x over previous
.Lmg_loop:
	s_waitcnt vmcnt(0)
	s_barrier
	s_add_i32 m0, s26, 0x8000
	s_nop 0
	global_load_lds_dwordx4 v194, s[8:9]
	s_add_i32 m0, s26, 0x9000
	s_nop 0
	global_load_lds_dwordx4 v195, s[8:9]
	s_add_i32 m0, s26, 0xa000
	s_nop 0
	global_load_lds_dwordx4 v194, s[10:11]
	s_add_i32 m0, s26, 0xb000
	s_nop 0
	global_load_lds_dwordx4 v195, s[10:11]
	s_add_i32 m0, s26, 0xc000
	s_nop 0
	global_load_lds_dwordx4 v194, s[12:13]
	s_add_i32 m0, s26, 0xd000
	s_nop 0
	global_load_lds_dwordx4 v195, s[12:13]
	s_add_i32 m0, s26, 0xe000
	s_nop 0
	global_load_lds_dwordx4 v194, s[36:37]
	s_add_i32 m0, s26, 0xf000
	s_nop 0
	global_load_lds_dwordx4 v195, s[36:37]
	v_add_u32_e32 v194, 64, v194
	v_add_u32_e32 v195, 64, v195
	ds_read_b128 v[228:231], v213 offset:0
	ds_read_b128 v[232:235], v213 offset:1024
	ds_read_b128 v[236:239], v213 offset:2048
	ds_read_b128 v[240:243], v213 offset:3072
	ds_read_b128 v[244:247], v214 offset:8192
	ds_read_b128 v[248:251], v214 offset:9216
	ds_read_b128 v[252:255], v214 offset:10240
	ds_read_b128 v[216:219], v214 offset:11264
	s_waitcnt lgkmcnt(3)
	s_setprio 1
	v_mfma_f32_16x16x32_bf16 v[2:5], v[244:247], v[228:231], v[2:5]
	v_mfma_f32_16x16x32_bf16 v[18:21], v[244:247], v[232:235], v[18:21]
	v_mfma_f32_16x16x32_bf16 v[34:37], v[244:247], v[236:239], v[34:37]
	v_mfma_f32_16x16x32_bf16 v[50:53], v[244:247], v[240:243], v[50:53]
	s_setprio 0
	ds_read_b128 v[244:247], v214 offset:16384
	s_waitcnt lgkmcnt(3)
	s_setprio 1
	v_mfma_f32_16x16x32_bf16 v[6:9], v[248:251], v[228:231], v[6:9]
	v_mfma_f32_16x16x32_bf16 v[22:25], v[248:251], v[232:235], v[22:25]
	v_mfma_f32_16x16x32_bf16 v[38:41], v[248:251], v[236:239], v[38:41]
	v_mfma_f32_16x16x32_bf16 v[54:57], v[248:251], v[240:243], v[54:57]
	s_setprio 0
	ds_read_b128 v[248:251], v214 offset:17408
	s_waitcnt lgkmcnt(3)
	s_setprio 1
	v_mfma_f32_16x16x32_bf16 v[10:13], v[252:255], v[228:231], v[10:13]
	v_mfma_f32_16x16x32_bf16 v[26:29], v[252:255], v[232:235], v[26:29]
	v_mfma_f32_16x16x32_bf16 v[42:45], v[252:255], v[236:239], v[42:45]
	v_mfma_f32_16x16x32_bf16 v[58:61], v[252:255], v[240:243], v[58:61]
	s_setprio 0
	ds_read_b128 v[252:255], v214 offset:18432
	s_waitcnt lgkmcnt(3)
	s_setprio 1
	v_mfma_f32_16x16x32_bf16 v[14:17], v[216:219], v[228:231], v[14:17]
	v_mfma_f32_16x16x32_bf16 v[30:33], v[216:219], v[232:235], v[30:33]
	v_mfma_f32_16x16x32_bf16 v[46:49], v[216:219], v[236:239], v[46:49]
	v_mfma_f32_16x16x32_bf16 v[62:65], v[216:219], v[240:243], v[62:65]
	s_setprio 0
	ds_read_b128 v[216:219], v214 offset:19456
	s_waitcnt lgkmcnt(3)
	s_setprio 1
	v_mfma_f32_16x16x32_bf16 v[66:69], v[244:247], v[228:231], v[66:69]
	v_mfma_f32_16x16x32_bf16 v[82:85], v[244:247], v[232:235], v[82:85]
	v_mfma_f32_16x16x32_bf16 v[98:101], v[244:247], v[236:239], v[98:101]
	v_mfma_f32_16x16x32_bf16 v[114:117], v[244:247], v[240:243], v[114:117]
	s_setprio 0
	ds_read_b128 v[244:247], v214 offset:24576
	s_waitcnt lgkmcnt(3)
	s_setprio 1
	v_mfma_f32_16x16x32_bf16 v[70:73], v[248:251], v[228:231], v[70:73]
	v_mfma_f32_16x16x32_bf16 v[86:89], v[248:251], v[232:235], v[86:89]
	v_mfma_f32_16x16x32_bf16 v[102:105], v[248:251], v[236:239], v[102:105]
	v_mfma_f32_16x16x32_bf16 v[118:121], v[248:251], v[240:243], v[118:121]
	s_setprio 0
	ds_read_b128 v[248:251], v214 offset:25600
	s_waitcnt lgkmcnt(3)
	s_setprio 1
	v_mfma_f32_16x16x32_bf16 v[74:77], v[252:255], v[228:231], v[74:77]
	v_mfma_f32_16x16x32_bf16 v[90:93], v[252:255], v[232:235], v[90:93]
	v_mfma_f32_16x16x32_bf16 v[106:109], v[252:255], v[236:239], v[106:109]
	v_mfma_f32_16x16x32_bf16 v[122:125], v[252:255], v[240:243], v[122:125]
	s_setprio 0
	ds_read_b128 v[252:255], v214 offset:26624
	s_waitcnt lgkmcnt(3)
	s_setprio 1
	v_mfma_f32_16x16x32_bf16 v[78:81], v[216:219], v[228:231], v[78:81]
	v_mfma_f32_16x16x32_bf16 v[94:97], v[216:219], v[232:235], v[94:97]
	v_mfma_f32_16x16x32_bf16 v[110:113], v[216:219], v[236:239], v[110:113]
	v_mfma_f32_16x16x32_bf16 v[126:129], v[216:219], v[240:243], v[126:129]
	s_setprio 0
	ds_read_b128 v[216:219], v214 offset:27648
	s_waitcnt lgkmcnt(3)
	s_setprio 1
	v_mfma_f32_16x16x32_bf16 v[130:133], v[244:247], v[228:231], v[130:133]
	v_mfma_f32_16x16x32_bf16 v[146:149], v[244:247], v[232:235], v[146:149]
	v_mfma_f32_16x16x32_bf16 v[162:165], v[244:247], v[236:239], v[162:165]
	v_mfma_f32_16x16x32_bf16 v[178:181], v[244:247], v[240:243], v[178:181]
	s_setprio 0
	s_waitcnt lgkmcnt(2)
	s_setprio 1
	v_mfma_f32_16x16x32_bf16 v[134:137], v[248:251], v[228:231], v[134:137]
	v_mfma_f32_16x16x32_bf16 v[150:153], v[248:251], v[232:235], v[150:153]
	v_mfma_f32_16x16x32_bf16 v[166:169], v[248:251], v[236:239], v[166:169]
	v_mfma_f32_16x16x32_bf16 v[182:185], v[248:251], v[240:243], v[182:185]
	s_setprio 0
	s_waitcnt lgkmcnt(1)
	s_setprio 1
	v_mfma_f32_16x16x32_bf16 v[138:141], v[252:255], v[228:231], v[138:141]
	v_mfma_f32_16x16x32_bf16 v[154:157], v[252:255], v[232:235], v[154:157]
	v_mfma_f32_16x16x32_bf16 v[170:173], v[252:255], v[236:239], v[170:173]
	v_mfma_f32_16x16x32_bf16 v[186:189], v[252:255], v[240:243], v[186:189]
	s_setprio 0
	s_waitcnt lgkmcnt(0)
	s_setprio 1
	v_mfma_f32_16x16x32_bf16 v[142:145], v[216:219], v[228:231], v[142:145]
	v_mfma_f32_16x16x32_bf16 v[158:161], v[216:219], v[232:235], v[158:161]
	v_mfma_f32_16x16x32_bf16 v[174:177], v[216:219], v[236:239], v[174:177]
	v_mfma_f32_16x16x32_bf16 v[190:193], v[216:219], v[240:243], v[190:193]
	s_setprio 0
	s_waitcnt vmcnt(0)
	s_barrier
	s_cmp_eq_u32 s27, 1
	s_cbranch_scc1 .Lmg_skip
	s_mov_b32 m0, s26
	s_nop 0
	global_load_lds_dwordx4 v194, s[8:9]
	s_add_i32 m0, s26, 0x1000
	s_nop 0
	global_load_lds_dwordx4 v195, s[8:9]
	s_add_i32 m0, s26, 0x2000
	s_nop 0
	global_load_lds_dwordx4 v194, s[10:11]
	s_add_i32 m0, s26, 0x3000
	s_nop 0
	global_load_lds_dwordx4 v195, s[10:11]
	s_add_i32 m0, s26, 0x4000
	s_nop 0
	global_load_lds_dwordx4 v194, s[12:13]
	s_add_i32 m0, s26, 0x5000
	s_nop 0
	global_load_lds_dwordx4 v195, s[12:13]
	s_add_i32 m0, s26, 0x6000
	s_nop 0
	global_load_lds_dwordx4 v194, s[36:37]
	s_add_i32 m0, s26, 0x7000
	s_nop 0
	global_load_lds_dwordx4 v195, s[36:37]
	v_add_u32_e32 v194, 64, v194
	v_add_u32_e32 v195, 64, v195
.Lmg_skip:
	ds_read_b128 v[228:231], v213 offset:32768
	ds_read_b128 v[232:235], v213 offset:33792
	ds_read_b128 v[236:239], v213 offset:34816
	ds_read_b128 v[240:243], v213 offset:35840
	ds_read_b128 v[244:247], v214 offset:40960
	ds_read_b128 v[248:251], v214 offset:41984
	ds_read_b128 v[252:255], v214 offset:43008
	ds_read_b128 v[216:219], v214 offset:44032
	s_waitcnt lgkmcnt(3)
	s_setprio 1
	v_mfma_f32_16x16x32_bf16 v[2:5], v[244:247], v[228:231], v[2:5]
	v_mfma_f32_16x16x32_bf16 v[18:21], v[244:247], v[232:235], v[18:21]
	v_mfma_f32_16x16x32_bf16 v[34:37], v[244:247], v[236:239], v[34:37]
	v_mfma_f32_16x16x32_bf16 v[50:53], v[244:247], v[240:243], v[50:53]
	s_setprio 0
	ds_read_b128 v[244:247], v214 offset:49152
	s_waitcnt lgkmcnt(3)
	s_setprio 1
	v_mfma_f32_16x16x32_bf16 v[6:9], v[248:251], v[228:231], v[6:9]
	v_mfma_f32_16x16x32_bf16 v[22:25], v[248:251], v[232:235], v[22:25]
	v_mfma_f32_16x16x32_bf16 v[38:41], v[248:251], v[236:239], v[38:41]
	v_mfma_f32_16x16x32_bf16 v[54:57], v[248:251], v[240:243], v[54:57]
	s_setprio 0
	ds_read_b128 v[248:251], v214 offset:50176
	s_waitcnt lgkmcnt(3)
	s_setprio 1
	v_mfma_f32_16x16x32_bf16 v[10:13], v[252:255], v[228:231], v[10:13]
	v_mfma_f32_16x16x32_bf16 v[26:29], v[252:255], v[232:235], v[26:29]
	v_mfma_f32_16x16x32_bf16 v[42:45], v[252:255], v[236:239], v[42:45]
	v_mfma_f32_16x16x32_bf16 v[58:61], v[252:255], v[240:243], v[58:61]
	s_setprio 0
	ds_read_b128 v[252:255], v214 offset:51200
	s_waitcnt lgkmcnt(3)
	s_setprio 1
	v_mfma_f32_16x16x32_bf16 v[14:17], v[216:219], v[228:231], v[14:17]
	v_mfma_f32_16x16x32_bf16 v[30:33], v[216:219], v[232:235], v[30:33]
	v_mfma_f32_16x16x32_bf16 v[46:49], v[216:219], v[236:239], v[46:49]
	v_mfma_f32_16x16x32_bf16 v[62:65], v[216:219], v[240:243], v[62:65]
	s_setprio 0
	ds_read_b128 v[216:219], v214 offset:52224
	s_waitcnt lgkmcnt(3)
	s_setprio 1
	v_mfma_f32_16x16x32_bf16 v[66:69], v[244:247], v[228:231], v[66:69]
	v_mfma_f32_16x16x32_bf16 v[82:85], v[244:247], v[232:235], v[82:85]
	v_mfma_f32_16x16x32_bf16 v[98:101], v[244:247], v[236:239], v[98:101]
	v_mfma_f32_16x16x32_bf16 v[114:117], v[244:247], v[240:243], v[114:117]
	s_setprio 0
	ds_read_b128 v[244:247], v214 offset:57344
	s_waitcnt lgkmcnt(3)
	s_setprio 1
	v_mfma_f32_16x16x32_bf16 v[70:73], v[248:251], v[228:231], v[70:73]
	v_mfma_f32_16x16x32_bf16 v[86:89], v[248:251], v[232:235], v[86:89]
	v_mfma_f32_16x16x32_bf16 v[102:105], v[248:251], v[236:239], v[102:105]
	v_mfma_f32_16x16x32_bf16 v[118:121], v[248:251], v[240:243], v[118:121]
	s_setprio 0
	ds_read_b128 v[248:251], v214 offset:58368
	s_waitcnt lgkmcnt(3)
	s_setprio 1
	v_mfma_f32_16x16x32_bf16 v[74:77], v[252:255], v[228:231], v[74:77]
	v_mfma_f32_16x16x32_bf16 v[90:93], v[252:255], v[232:235], v[90:93]
	v_mfma_f32_16x16x32_bf16 v[106:109], v[252:255], v[236:239], v[106:109]
	v_mfma_f32_16x16x32_bf16 v[122:125], v[252:255], v[240:243], v[122:125]
	s_setprio 0
	ds_read_b128 v[252:255], v214 offset:59392
	s_waitcnt lgkmcnt(3)
	s_setprio 1
	v_mfma_f32_16x16x32_bf16 v[78:81], v[216:219], v[228:231], v[78:81]
	v_mfma_f32_16x16x32_bf16 v[94:97], v[216:219], v[232:235], v[94:97]
	v_mfma_f32_16x16x32_bf16 v[110:113], v[216:219], v[236:239], v[110:113]
	v_mfma_f32_16x16x32_bf16 v[126:129], v[216:219], v[240:243], v[126:129]
	s_setprio 0
	ds_read_b128 v[216:219], v214 offset:60416
	s_waitcnt lgkmcnt(3)
	s_setprio 1
	v_mfma_f32_16x16x32_bf16 v[130:133], v[244:247], v[228:231], v[130:133]
	v_mfma_f32_16x16x32_bf16 v[146:149], v[244:247], v[232:235], v[146:149]
	v_mfma_f32_16x16x32_bf16 v[162:165], v[244:247], v[236:239], v[162:165]
	v_mfma_f32_16x16x32_bf16 v[178:181], v[244:247], v[240:243], v[178:181]
	s_setprio 0
	s_waitcnt lgkmcnt(2)
	s_setprio 1
	v_mfma_f32_16x16x32_bf16 v[134:137], v[248:251], v[228:231], v[134:137]
	v_mfma_f32_16x16x32_bf16 v[150:153], v[248:251], v[232:235], v[150:153]
	v_mfma_f32_16x16x32_bf16 v[166:169], v[248:251], v[236:239], v[166:169]
	v_mfma_f32_16x16x32_bf16 v[182:185], v[248:251], v[240:243], v[182:185]
	s_setprio 0
	s_waitcnt lgkmcnt(1)
	s_setprio 1
	v_mfma_f32_16x16x32_bf16 v[138:141], v[252:255], v[228:231], v[138:141]
	v_mfma_f32_16x16x32_bf16 v[154:157], v[252:255], v[232:235], v[154:157]
	v_mfma_f32_16x16x32_bf16 v[170:173], v[252:255], v[236:239], v[170:173]
	v_mfma_f32_16x16x32_bf16 v[186:189], v[252:255], v[240:243], v[186:189]
	s_setprio 0
	s_waitcnt lgkmcnt(0)
	s_setprio 1
	v_mfma_f32_16x16x32_bf16 v[142:145], v[216:219], v[228:231], v[142:145]
	v_mfma_f32_16x16x32_bf16 v[158:161], v[216:219], v[232:235], v[158:161]
	v_mfma_f32_16x16x32_bf16 v[174:177], v[216:219], v[236:239], v[174:177]
	v_mfma_f32_16x16x32_bf16 v[190:193], v[216:219], v[240:243], v[190:193]
	s_setprio 0
	s_sub_u32 s27, s27, 1
	s_cmp_lg_u32 s27, 0
	s_cbranch_scc1 .Lmg_loop
	s_barrier
	v_and_b32_e32 v213, 15, v196
	v_lshrrev_b32_e32 v214, 7, v196
	v_lshl_add_u32 v213, v214, 6, v213
	v_bfe_u32 v214, v196, 6, 1
	v_bfe_u32 v220, v196, 4, 2
	v_lshlrev_b32_e32 v220, 3, v220
	v_lshl_add_u32 v214, v214, 7, v220
	v_lshl_add_u32 v215, v213, 11, v214
	v_add_u32_e32 v220, 0x8000, v215
	v_add_u32_e32 v227, 0x10000, v215
	v_add_u32_e32 v0, 0x18000, v215
	s_add_u32 s38, s19, s2
	s_addc_u32 s39, s20, 0
	s_nop 0
	global_load_dwordx2 v[228:229], v215, s[38:39] offset:0
	global_load_dwordx2 v[230:231], v215, s[38:39] offset:32
	global_load_dwordx2 v[232:233], v215, s[38:39] offset:64
	global_load_dwordx2 v[234:235], v215, s[38:39] offset:96
	global_load_dwordx2 v[236:237], v220, s[38:39] offset:0
	global_load_dwordx2 v[238:239], v220, s[38:39] offset:32
	global_load_dwordx2 v[240:241], v220, s[38:39] offset:64
	global_load_dwordx2 v[242:243], v220, s[38:39] offset:96
	global_load_dwordx2 v[244:245], v227, s[38:39] offset:0
	global_load_dwordx2 v[246:247], v227, s[38:39] offset:32
	global_load_dwordx2 v[248:249], v227, s[38:39] offset:64
	global_load_dwordx2 v[250:251], v227, s[38:39] offset:96
	global_load_dwordx2 v[252:253], v0, s[38:39] offset:0
	global_load_dwordx2 v[254:255], v0, s[38:39] offset:32
	global_load_dwordx2 v[216:217], v0, s[38:39] offset:64
	global_load_dwordx2 v[218:219], v0, s[38:39] offset:96
	v_mul_f32_e32 v2, 0xbfb8aa3b, v2
	v_mul_f32_e32 v3, 0xbfb8aa3b, v3
	v_mul_f32_e32 v4, 0xbfb8aa3b, v4
	v_mul_f32_e32 v5, 0xbfb8aa3b, v5
	v_exp_f32_e32 v2, v2
	v_exp_f32_e32 v3, v3
	v_exp_f32_e32 v4, v4
	v_exp_f32_e32 v5, v5
	v_add_f32_e32 v2, 1.0, v2
	v_add_f32_e32 v3, 1.0, v3
	v_add_f32_e32 v4, 1.0, v4
	v_add_f32_e32 v5, 1.0, v5
	v_rcp_f32_e32 v2, v2
	v_rcp_f32_e32 v3, v3
	v_rcp_f32_e32 v4, v4
	v_rcp_f32_e32 v5, v5
	v_mul_f32_e32 v6, 0xbfb8aa3b, v6
	v_mul_f32_e32 v7, 0xbfb8aa3b, v7
	v_mul_f32_e32 v8, 0xbfb8aa3b, v8
	v_mul_f32_e32 v9, 0xbfb8aa3b, v9
	v_exp_f32_e32 v6, v6
	v_exp_f32_e32 v7, v7
	v_exp_f32_e32 v8, v8
	v_exp_f32_e32 v9, v9
	v_add_f32_e32 v6, 1.0, v6
	v_add_f32_e32 v7, 1.0, v7
	v_add_f32_e32 v8, 1.0, v8
	v_add_f32_e32 v9, 1.0, v9
	v_rcp_f32_e32 v6, v6
	v_rcp_f32_e32 v7, v7
	v_rcp_f32_e32 v8, v8
	v_rcp_f32_e32 v9, v9
	v_mul_f32_e32 v10, 0xbfb8aa3b, v10
	v_mul_f32_e32 v11, 0xbfb8aa3b, v11
	v_mul_f32_e32 v12, 0xbfb8aa3b, v12
	v_mul_f32_e32 v13, 0xbfb8aa3b, v13
	v_exp_f32_e32 v10, v10
	v_exp_f32_e32 v11, v11
	v_exp_f32_e32 v12, v12
	v_exp_f32_e32 v13, v13
	v_add_f32_e32 v10, 1.0, v10
	v_add_f32_e32 v11, 1.0, v11
	v_add_f32_e32 v12, 1.0, v12
	v_add_f32_e32 v13, 1.0, v13
	v_rcp_f32_e32 v10, v10
	v_rcp_f32_e32 v11, v11
	v_rcp_f32_e32 v12, v12
	v_rcp_f32_e32 v13, v13
	v_mul_f32_e32 v14, 0xbfb8aa3b, v14
	v_mul_f32_e32 v15, 0xbfb8aa3b, v15
	v_mul_f32_e32 v16, 0xbfb8aa3b, v16
	v_mul_f32_e32 v17, 0xbfb8aa3b, v17
	v_exp_f32_e32 v14, v14
	v_exp_f32_e32 v15, v15
	v_exp_f32_e32 v16, v16
	v_exp_f32_e32 v17, v17
	v_add_f32_e32 v14, 1.0, v14
	v_add_f32_e32 v15, 1.0, v15
	v_add_f32_e32 v16, 1.0, v16
	v_add_f32_e32 v17, 1.0, v17
	v_rcp_f32_e32 v14, v14
	v_rcp_f32_e32 v15, v15
	v_rcp_f32_e32 v16, v16
	v_rcp_f32_e32 v17, v17
	v_mul_f32_e32 v18, 0xbfb8aa3b, v18
	v_mul_f32_e32 v19, 0xbfb8aa3b, v19
	v_mul_f32_e32 v20, 0xbfb8aa3b, v20
	v_mul_f32_e32 v21, 0xbfb8aa3b, v21
	v_exp_f32_e32 v18, v18
	v_exp_f32_e32 v19, v19
	v_exp_f32_e32 v20, v20
	v_exp_f32_e32 v21, v21
	v_add_f32_e32 v18, 1.0, v18
	v_add_f32_e32 v19, 1.0, v19
	v_add_f32_e32 v20, 1.0, v20
	v_add_f32_e32 v21, 1.0, v21
	v_rcp_f32_e32 v18, v18
	v_rcp_f32_e32 v19, v19
	v_rcp_f32_e32 v20, v20
	v_rcp_f32_e32 v21, v21
	v_mul_f32_e32 v22, 0xbfb8aa3b, v22
	v_mul_f32_e32 v23, 0xbfb8aa3b, v23
	v_mul_f32_e32 v24, 0xbfb8aa3b, v24
	v_mul_f32_e32 v25, 0xbfb8aa3b, v25
	v_exp_f32_e32 v22, v22
	v_exp_f32_e32 v23, v23
	v_exp_f32_e32 v24, v24
	v_exp_f32_e32 v25, v25
	v_add_f32_e32 v22, 1.0, v22
	v_add_f32_e32 v23, 1.0, v23
	v_add_f32_e32 v24, 1.0, v24
	v_add_f32_e32 v25, 1.0, v25
	v_rcp_f32_e32 v22, v22
	v_rcp_f32_e32 v23, v23
	v_rcp_f32_e32 v24, v24
	v_rcp_f32_e32 v25, v25
	v_mul_f32_e32 v26, 0xbfb8aa3b, v26
	v_mul_f32_e32 v27, 0xbfb8aa3b, v27
	v_mul_f32_e32 v28, 0xbfb8aa3b, v28
	v_mul_f32_e32 v29, 0xbfb8aa3b, v29
	v_exp_f32_e32 v26, v26
	v_exp_f32_e32 v27, v27
	v_exp_f32_e32 v28, v28
	v_exp_f32_e32 v29, v29
	v_add_f32_e32 v26, 1.0, v26
	v_add_f32_e32 v27, 1.0, v27
	v_add_f32_e32 v28, 1.0, v28
	v_add_f32_e32 v29, 1.0, v29
	v_rcp_f32_e32 v26, v26
	v_rcp_f32_e32 v27, v27
	v_rcp_f32_e32 v28, v28
	v_rcp_f32_e32 v29, v29
	v_mul_f32_e32 v30, 0xbfb8aa3b, v30
	v_mul_f32_e32 v31, 0xbfb8aa3b, v31
	v_mul_f32_e32 v32, 0xbfb8aa3b, v32
	v_mul_f32_e32 v33, 0xbfb8aa3b, v33
	v_exp_f32_e32 v30, v30
	v_exp_f32_e32 v31, v31
	v_exp_f32_e32 v32, v32
	v_exp_f32_e32 v33, v33
	v_add_f32_e32 v30, 1.0, v30
	v_add_f32_e32 v31, 1.0, v31
	v_add_f32_e32 v32, 1.0, v32
	v_add_f32_e32 v33, 1.0, v33
	v_rcp_f32_e32 v30, v30
	v_rcp_f32_e32 v31, v31
	v_rcp_f32_e32 v32, v32
	v_rcp_f32_e32 v33, v33
	v_mul_f32_e32 v34, 0xbfb8aa3b, v34
	v_mul_f32_e32 v35, 0xbfb8aa3b, v35
	v_mul_f32_e32 v36, 0xbfb8aa3b, v36
	v_mul_f32_e32 v37, 0xbfb8aa3b, v37
	v_exp_f32_e32 v34, v34
	v_exp_f32_e32 v35, v35
	v_exp_f32_e32 v36, v36
	v_exp_f32_e32 v37, v37
	v_add_f32_e32 v34, 1.0, v34
	v_add_f32_e32 v35, 1.0, v35
	v_add_f32_e32 v36, 1.0, v36
	v_add_f32_e32 v37, 1.0, v37
	v_rcp_f32_e32 v34, v34
	v_rcp_f32_e32 v35, v35
	v_rcp_f32_e32 v36, v36
	v_rcp_f32_e32 v37, v37
	v_mul_f32_e32 v38, 0xbfb8aa3b, v38
	v_mul_f32_e32 v39, 0xbfb8aa3b, v39
	v_mul_f32_e32 v40, 0xbfb8aa3b, v40
	v_mul_f32_e32 v41, 0xbfb8aa3b, v41
	v_exp_f32_e32 v38, v38
	v_exp_f32_e32 v39, v39
	v_exp_f32_e32 v40, v40
	v_exp_f32_e32 v41, v41
	v_add_f32_e32 v38, 1.0, v38
	v_add_f32_e32 v39, 1.0, v39
	v_add_f32_e32 v40, 1.0, v40
	v_add_f32_e32 v41, 1.0, v41
	v_rcp_f32_e32 v38, v38
	v_rcp_f32_e32 v39, v39
	v_rcp_f32_e32 v40, v40
	v_rcp_f32_e32 v41, v41
	v_mul_f32_e32 v42, 0xbfb8aa3b, v42
	v_mul_f32_e32 v43, 0xbfb8aa3b, v43
	v_mul_f32_e32 v44, 0xbfb8aa3b, v44
	v_mul_f32_e32 v45, 0xbfb8aa3b, v45
	v_exp_f32_e32 v42, v42
	v_exp_f32_e32 v43, v43
	v_exp_f32_e32 v44, v44
	v_exp_f32_e32 v45, v45
	v_add_f32_e32 v42, 1.0, v42
	v_add_f32_e32 v43, 1.0, v43
	v_add_f32_e32 v44, 1.0, v44
	v_add_f32_e32 v45, 1.0, v45
	v_rcp_f32_e32 v42, v42
	v_rcp_f32_e32 v43, v43
	v_rcp_f32_e32 v44, v44
	v_rcp_f32_e32 v45, v45
	v_mul_f32_e32 v46, 0xbfb8aa3b, v46
	v_mul_f32_e32 v47, 0xbfb8aa3b, v47
	v_mul_f32_e32 v48, 0xbfb8aa3b, v48
	v_mul_f32_e32 v49, 0xbfb8aa3b, v49
	v_exp_f32_e32 v46, v46
	v_exp_f32_e32 v47, v47
	v_exp_f32_e32 v48, v48
	v_exp_f32_e32 v49, v49
	v_add_f32_e32 v46, 1.0, v46
	v_add_f32_e32 v47, 1.0, v47
	v_add_f32_e32 v48, 1.0, v48
	v_add_f32_e32 v49, 1.0, v49
	v_rcp_f32_e32 v46, v46
	v_rcp_f32_e32 v47, v47
	v_rcp_f32_e32 v48, v48
	v_rcp_f32_e32 v49, v49
	v_mul_f32_e32 v50, 0xbfb8aa3b, v50
	v_mul_f32_e32 v51, 0xbfb8aa3b, v51
	v_mul_f32_e32 v52, 0xbfb8aa3b, v52
	v_mul_f32_e32 v53, 0xbfb8aa3b, v53
	v_exp_f32_e32 v50, v50
	v_exp_f32_e32 v51, v51
	v_exp_f32_e32 v52, v52
	v_exp_f32_e32 v53, v53
	v_add_f32_e32 v50, 1.0, v50
	v_add_f32_e32 v51, 1.0, v51
	v_add_f32_e32 v52, 1.0, v52
	v_add_f32_e32 v53, 1.0, v53
	v_rcp_f32_e32 v50, v50
	v_rcp_f32_e32 v51, v51
	v_rcp_f32_e32 v52, v52
	v_rcp_f32_e32 v53, v53
	v_mul_f32_e32 v54, 0xbfb8aa3b, v54
	v_mul_f32_e32 v55, 0xbfb8aa3b, v55
	v_mul_f32_e32 v56, 0xbfb8aa3b, v56
	v_mul_f32_e32 v57, 0xbfb8aa3b, v57
	v_exp_f32_e32 v54, v54
	v_exp_f32_e32 v55, v55
	v_exp_f32_e32 v56, v56
	v_exp_f32_e32 v57, v57
	v_add_f32_e32 v54, 1.0, v54
	v_add_f32_e32 v55, 1.0, v55
	v_add_f32_e32 v56, 1.0, v56
	v_add_f32_e32 v57, 1.0, v57
	v_rcp_f32_e32 v54, v54
	v_rcp_f32_e32 v55, v55
	v_rcp_f32_e32 v56, v56
	v_rcp_f32_e32 v57, v57
	v_mul_f32_e32 v58, 0xbfb8aa3b, v58
	v_mul_f32_e32 v59, 0xbfb8aa3b, v59
	v_mul_f32_e32 v60, 0xbfb8aa3b, v60
	v_mul_f32_e32 v61, 0xbfb8aa3b, v61
	v_exp_f32_e32 v58, v58
	v_exp_f32_e32 v59, v59
	v_exp_f32_e32 v60, v60
	v_exp_f32_e32 v61, v61
	v_add_f32_e32 v58, 1.0, v58
	v_add_f32_e32 v59, 1.0, v59
	v_add_f32_e32 v60, 1.0, v60
	v_add_f32_e32 v61, 1.0, v61
	v_rcp_f32_e32 v58, v58
	v_rcp_f32_e32 v59, v59
	v_rcp_f32_e32 v60, v60
	v_rcp_f32_e32 v61, v61
	v_mul_f32_e32 v62, 0xbfb8aa3b, v62
	v_mul_f32_e32 v63, 0xbfb8aa3b, v63
	v_mul_f32_e32 v64, 0xbfb8aa3b, v64
	v_mul_f32_e32 v65, 0xbfb8aa3b, v65
	v_exp_f32_e32 v62, v62
	v_exp_f32_e32 v63, v63
	v_exp_f32_e32 v64, v64
	v_exp_f32_e32 v65, v65
	v_add_f32_e32 v62, 1.0, v62
	v_add_f32_e32 v63, 1.0, v63
	v_add_f32_e32 v64, 1.0, v64
	v_add_f32_e32 v65, 1.0, v65
	v_rcp_f32_e32 v62, v62
	v_rcp_f32_e32 v63, v63
	v_rcp_f32_e32 v64, v64
	v_rcp_f32_e32 v65, v65
	s_waitcnt vmcnt(0)
	v_lshlrev_b32_e32 v194, 16, v228
	v_and_b32_e32 v195, 0xffff0000, v228
	v_lshlrev_b32_e32 v213, 16, v229
	v_and_b32_e32 v214, 0xffff0000, v229
	v_fma_f32 v2, v194, v2, v1
	v_fma_f32 v3, v195, v3, v1
	v_fma_f32 v4, v213, v4, v1
	v_fma_f32 v5, v214, v5, v1
	v_lshlrev_b32_e32 v194, 16, v230
	v_and_b32_e32 v195, 0xffff0000, v230
	v_lshlrev_b32_e32 v213, 16, v231
	v_and_b32_e32 v214, 0xffff0000, v231
	v_fma_f32 v6, v194, v6, v1
	v_fma_f32 v7, v195, v7, v1
	v_fma_f32 v8, v213, v8, v1
	v_fma_f32 v9, v214, v9, v1
	v_lshlrev_b32_e32 v194, 16, v232
	v_and_b32_e32 v195, 0xffff0000, v232
	v_lshlrev_b32_e32 v213, 16, v233
	v_and_b32_e32 v214, 0xffff0000, v233
	v_fma_f32 v10, v194, v10, v1
	v_fma_f32 v11, v195, v11, v1
	v_fma_f32 v12, v213, v12, v1
	v_fma_f32 v13, v214, v13, v1
	v_lshlrev_b32_e32 v194, 16, v234
	v_and_b32_e32 v195, 0xffff0000, v234
	v_lshlrev_b32_e32 v213, 16, v235
	v_and_b32_e32 v214, 0xffff0000, v235
	v_fma_f32 v14, v194, v14, v1
	v_fma_f32 v15, v195, v15, v1
	v_fma_f32 v16, v213, v16, v1
	v_fma_f32 v17, v214, v17, v1
	v_lshlrev_b32_e32 v194, 16, v236
	v_and_b32_e32 v195, 0xffff0000, v236
	v_lshlrev_b32_e32 v213, 16, v237
	v_and_b32_e32 v214, 0xffff0000, v237
	v_fma_f32 v18, v194, v18, v1
	v_fma_f32 v19, v195, v19, v1
	v_fma_f32 v20, v213, v20, v1
	v_fma_f32 v21, v214, v21, v1
	v_lshlrev_b32_e32 v194, 16, v238
	v_and_b32_e32 v195, 0xffff0000, v238
	v_lshlrev_b32_e32 v213, 16, v239
	v_and_b32_e32 v214, 0xffff0000, v239
	v_fma_f32 v22, v194, v22, v1
	v_fma_f32 v23, v195, v23, v1
	v_fma_f32 v24, v213, v24, v1
	v_fma_f32 v25, v214, v25, v1
	v_lshlrev_b32_e32 v194, 16, v240
	v_and_b32_e32 v195, 0xffff0000, v240
	v_lshlrev_b32_e32 v213, 16, v241
	v_and_b32_e32 v214, 0xffff0000, v241
	v_fma_f32 v26, v194, v26, v1
	v_fma_f32 v27, v195, v27, v1
	v_fma_f32 v28, v213, v28, v1
	v_fma_f32 v29, v214, v29, v1
	v_lshlrev_b32_e32 v194, 16, v242
	v_and_b32_e32 v195, 0xffff0000, v242
	v_lshlrev_b32_e32 v213, 16, v243
	v_and_b32_e32 v214, 0xffff0000, v243
	v_fma_f32 v30, v194, v30, v1
	v_fma_f32 v31, v195, v31, v1
	v_fma_f32 v32, v213, v32, v1
	v_fma_f32 v33, v214, v33, v1
	v_lshlrev_b32_e32 v194, 16, v244
	v_and_b32_e32 v195, 0xffff0000, v244
	v_lshlrev_b32_e32 v213, 16, v245
	v_and_b32_e32 v214, 0xffff0000, v245
	v_fma_f32 v34, v194, v34, v1
	v_fma_f32 v35, v195, v35, v1
	v_fma_f32 v36, v213, v36, v1
	v_fma_f32 v37, v214, v37, v1
	v_lshlrev_b32_e32 v194, 16, v246
	v_and_b32_e32 v195, 0xffff0000, v246
	v_lshlrev_b32_e32 v213, 16, v247
	v_and_b32_e32 v214, 0xffff0000, v247
	v_fma_f32 v38, v194, v38, v1
	v_fma_f32 v39, v195, v39, v1
	v_fma_f32 v40, v213, v40, v1
	v_fma_f32 v41, v214, v41, v1
	v_lshlrev_b32_e32 v194, 16, v248
	v_and_b32_e32 v195, 0xffff0000, v248
	v_lshlrev_b32_e32 v213, 16, v249
	v_and_b32_e32 v214, 0xffff0000, v249
	v_fma_f32 v42, v194, v42, v1
	v_fma_f32 v43, v195, v43, v1
	v_fma_f32 v44, v213, v44, v1
	v_fma_f32 v45, v214, v45, v1
	v_lshlrev_b32_e32 v194, 16, v250
	v_and_b32_e32 v195, 0xffff0000, v250
	v_lshlrev_b32_e32 v213, 16, v251
	v_and_b32_e32 v214, 0xffff0000, v251
	v_fma_f32 v46, v194, v46, v1
	v_fma_f32 v47, v195, v47, v1
	v_fma_f32 v48, v213, v48, v1
	v_fma_f32 v49, v214, v49, v1
	v_lshlrev_b32_e32 v194, 16, v252
	v_and_b32_e32 v195, 0xffff0000, v252
	v_lshlrev_b32_e32 v213, 16, v253
	v_and_b32_e32 v214, 0xffff0000, v253
	v_fma_f32 v50, v194, v50, v1
	v_fma_f32 v51, v195, v51, v1
	v_fma_f32 v52, v213, v52, v1
	v_fma_f32 v53, v214, v53, v1
	v_lshlrev_b32_e32 v194, 16, v254
	v_and_b32_e32 v195, 0xffff0000, v254
	v_lshlrev_b32_e32 v213, 16, v255
	v_and_b32_e32 v214, 0xffff0000, v255
	v_fma_f32 v54, v194, v54, v1
	v_fma_f32 v55, v195, v55, v1
	v_fma_f32 v56, v213, v56, v1
	v_fma_f32 v57, v214, v57, v1
	v_lshlrev_b32_e32 v194, 16, v216
	v_and_b32_e32 v195, 0xffff0000, v216
	v_lshlrev_b32_e32 v213, 16, v217
	v_and_b32_e32 v214, 0xffff0000, v217
	v_fma_f32 v58, v194, v58, v1
	v_fma_f32 v59, v195, v59, v1
	v_fma_f32 v60, v213, v60, v1
	v_fma_f32 v61, v214, v61, v1
	v_lshlrev_b32_e32 v194, 16, v218
	v_and_b32_e32 v195, 0xffff0000, v218
	v_lshlrev_b32_e32 v213, 16, v219
	v_and_b32_e32 v214, 0xffff0000, v219
	v_fma_f32 v62, v194, v62, v1
	v_fma_f32 v63, v195, v63, v1
	v_fma_f32 v64, v213, v64, v1
	v_fma_f32 v65, v214, v65, v1
	s_add_u32 s38, s42, 0x1241c000
	s_addc_u32 s39, s43, 0
	s_add_u32 s38, s38, s2
	s_addc_u32 s39, s39, 0
	s_nop 0
	global_load_dwordx2 v[228:229], v215, s[38:39] offset:0
	global_load_dwordx2 v[230:231], v215, s[38:39] offset:32
	global_load_dwordx2 v[232:233], v215, s[38:39] offset:64
	global_load_dwordx2 v[234:235], v215, s[38:39] offset:96
	global_load_dwordx2 v[236:237], v220, s[38:39] offset:0
	global_load_dwordx2 v[238:239], v220, s[38:39] offset:32
	global_load_dwordx2 v[240:241], v220, s[38:39] offset:64
	global_load_dwordx2 v[242:243], v220, s[38:39] offset:96
	global_load_dwordx2 v[244:245], v227, s[38:39] offset:0
	global_load_dwordx2 v[246:247], v227, s[38:39] offset:32
	global_load_dwordx2 v[248:249], v227, s[38:39] offset:64
	global_load_dwordx2 v[250:251], v227, s[38:39] offset:96
	global_load_dwordx2 v[252:253], v0, s[38:39] offset:0
	global_load_dwordx2 v[254:255], v0, s[38:39] offset:32
	global_load_dwordx2 v[216:217], v0, s[38:39] offset:64
	global_load_dwordx2 v[218:219], v0, s[38:39] offset:96
	v_mul_f32_e32 v66, 0xbfb8aa3b, v66
	v_mul_f32_e32 v67, 0xbfb8aa3b, v67
	v_mul_f32_e32 v68, 0xbfb8aa3b, v68
	v_mul_f32_e32 v69, 0xbfb8aa3b, v69
	v_exp_f32_e32 v66, v66
	v_exp_f32_e32 v67, v67
	v_exp_f32_e32 v68, v68
	v_exp_f32_e32 v69, v69
	v_add_f32_e32 v66, 1.0, v66
	v_add_f32_e32 v67, 1.0, v67
	v_add_f32_e32 v68, 1.0, v68
	v_add_f32_e32 v69, 1.0, v69
	v_rcp_f32_e32 v66, v66
	v_rcp_f32_e32 v67, v67
	v_rcp_f32_e32 v68, v68
	v_rcp_f32_e32 v69, v69
	v_mul_f32_e32 v70, 0xbfb8aa3b, v70
	v_mul_f32_e32 v71, 0xbfb8aa3b, v71
	v_mul_f32_e32 v72, 0xbfb8aa3b, v72
	v_mul_f32_e32 v73, 0xbfb8aa3b, v73
	v_exp_f32_e32 v70, v70
	v_exp_f32_e32 v71, v71
	v_exp_f32_e32 v72, v72
	v_exp_f32_e32 v73, v73
	v_add_f32_e32 v70, 1.0, v70
	v_add_f32_e32 v71, 1.0, v71
	v_add_f32_e32 v72, 1.0, v72
	v_add_f32_e32 v73, 1.0, v73
	v_rcp_f32_e32 v70, v70
	v_rcp_f32_e32 v71, v71
	v_rcp_f32_e32 v72, v72
	v_rcp_f32_e32 v73, v73
	v_mul_f32_e32 v74, 0xbfb8aa3b, v74
	v_mul_f32_e32 v75, 0xbfb8aa3b, v75
	v_mul_f32_e32 v76, 0xbfb8aa3b, v76
	v_mul_f32_e32 v77, 0xbfb8aa3b, v77
	v_exp_f32_e32 v74, v74
	v_exp_f32_e32 v75, v75
	v_exp_f32_e32 v76, v76
	v_exp_f32_e32 v77, v77
	v_add_f32_e32 v74, 1.0, v74
	v_add_f32_e32 v75, 1.0, v75
	v_add_f32_e32 v76, 1.0, v76
	v_add_f32_e32 v77, 1.0, v77
	v_rcp_f32_e32 v74, v74
	v_rcp_f32_e32 v75, v75
	v_rcp_f32_e32 v76, v76
	v_rcp_f32_e32 v77, v77
	v_mul_f32_e32 v78, 0xbfb8aa3b, v78
	v_mul_f32_e32 v79, 0xbfb8aa3b, v79
	v_mul_f32_e32 v80, 0xbfb8aa3b, v80
	v_mul_f32_e32 v81, 0xbfb8aa3b, v81
	v_exp_f32_e32 v78, v78
	v_exp_f32_e32 v79, v79
	v_exp_f32_e32 v80, v80
	v_exp_f32_e32 v81, v81
	v_add_f32_e32 v78, 1.0, v78
	v_add_f32_e32 v79, 1.0, v79
	v_add_f32_e32 v80, 1.0, v80
	v_add_f32_e32 v81, 1.0, v81
	v_rcp_f32_e32 v78, v78
	v_rcp_f32_e32 v79, v79
	v_rcp_f32_e32 v80, v80
	v_rcp_f32_e32 v81, v81
	v_mul_f32_e32 v82, 0xbfb8aa3b, v82
	v_mul_f32_e32 v83, 0xbfb8aa3b, v83
	v_mul_f32_e32 v84, 0xbfb8aa3b, v84
	v_mul_f32_e32 v85, 0xbfb8aa3b, v85
	v_exp_f32_e32 v82, v82
	v_exp_f32_e32 v83, v83
	v_exp_f32_e32 v84, v84
	v_exp_f32_e32 v85, v85
	v_add_f32_e32 v82, 1.0, v82
	v_add_f32_e32 v83, 1.0, v83
	v_add_f32_e32 v84, 1.0, v84
	v_add_f32_e32 v85, 1.0, v85
	v_rcp_f32_e32 v82, v82
	v_rcp_f32_e32 v83, v83
	v_rcp_f32_e32 v84, v84
	v_rcp_f32_e32 v85, v85
	v_mul_f32_e32 v86, 0xbfb8aa3b, v86
	v_mul_f32_e32 v87, 0xbfb8aa3b, v87
	v_mul_f32_e32 v88, 0xbfb8aa3b, v88
	v_mul_f32_e32 v89, 0xbfb8aa3b, v89
	v_exp_f32_e32 v86, v86
	v_exp_f32_e32 v87, v87
	v_exp_f32_e32 v88, v88
	v_exp_f32_e32 v89, v89
	v_add_f32_e32 v86, 1.0, v86
	v_add_f32_e32 v87, 1.0, v87
	v_add_f32_e32 v88, 1.0, v88
	v_add_f32_e32 v89, 1.0, v89
	v_rcp_f32_e32 v86, v86
	v_rcp_f32_e32 v87, v87
	v_rcp_f32_e32 v88, v88
	v_rcp_f32_e32 v89, v89
	v_mul_f32_e32 v90, 0xbfb8aa3b, v90
	v_mul_f32_e32 v91, 0xbfb8aa3b, v91
	v_mul_f32_e32 v92, 0xbfb8aa3b, v92
	v_mul_f32_e32 v93, 0xbfb8aa3b, v93
	v_exp_f32_e32 v90, v90
	v_exp_f32_e32 v91, v91
	v_exp_f32_e32 v92, v92
	v_exp_f32_e32 v93, v93
	v_add_f32_e32 v90, 1.0, v90
	v_add_f32_e32 v91, 1.0, v91
	v_add_f32_e32 v92, 1.0, v92
	v_add_f32_e32 v93, 1.0, v93
	v_rcp_f32_e32 v90, v90
	v_rcp_f32_e32 v91, v91
	v_rcp_f32_e32 v92, v92
	v_rcp_f32_e32 v93, v93
	v_mul_f32_e32 v94, 0xbfb8aa3b, v94
	v_mul_f32_e32 v95, 0xbfb8aa3b, v95
	v_mul_f32_e32 v96, 0xbfb8aa3b, v96
	v_mul_f32_e32 v97, 0xbfb8aa3b, v97
	v_exp_f32_e32 v94, v94
	v_exp_f32_e32 v95, v95
	v_exp_f32_e32 v96, v96
	v_exp_f32_e32 v97, v97
	v_add_f32_e32 v94, 1.0, v94
	v_add_f32_e32 v95, 1.0, v95
	v_add_f32_e32 v96, 1.0, v96
	v_add_f32_e32 v97, 1.0, v97
	v_rcp_f32_e32 v94, v94
	v_rcp_f32_e32 v95, v95
	v_rcp_f32_e32 v96, v96
	v_rcp_f32_e32 v97, v97
	v_mul_f32_e32 v98, 0xbfb8aa3b, v98
	v_mul_f32_e32 v99, 0xbfb8aa3b, v99
	v_mul_f32_e32 v100, 0xbfb8aa3b, v100
	v_mul_f32_e32 v101, 0xbfb8aa3b, v101
	v_exp_f32_e32 v98, v98
	v_exp_f32_e32 v99, v99
	v_exp_f32_e32 v100, v100
	v_exp_f32_e32 v101, v101
	v_add_f32_e32 v98, 1.0, v98
	v_add_f32_e32 v99, 1.0, v99
	v_add_f32_e32 v100, 1.0, v100
	v_add_f32_e32 v101, 1.0, v101
	v_rcp_f32_e32 v98, v98
	v_rcp_f32_e32 v99, v99
	v_rcp_f32_e32 v100, v100
	v_rcp_f32_e32 v101, v101
	v_mul_f32_e32 v102, 0xbfb8aa3b, v102
	v_mul_f32_e32 v103, 0xbfb8aa3b, v103
	v_mul_f32_e32 v104, 0xbfb8aa3b, v104
	v_mul_f32_e32 v105, 0xbfb8aa3b, v105
	v_exp_f32_e32 v102, v102
	v_exp_f32_e32 v103, v103
	v_exp_f32_e32 v104, v104
	v_exp_f32_e32 v105, v105
	v_add_f32_e32 v102, 1.0, v102
	v_add_f32_e32 v103, 1.0, v103
	v_add_f32_e32 v104, 1.0, v104
	v_add_f32_e32 v105, 1.0, v105
	v_rcp_f32_e32 v102, v102
	v_rcp_f32_e32 v103, v103
	v_rcp_f32_e32 v104, v104
	v_rcp_f32_e32 v105, v105
	v_mul_f32_e32 v106, 0xbfb8aa3b, v106
	v_mul_f32_e32 v107, 0xbfb8aa3b, v107
	v_mul_f32_e32 v108, 0xbfb8aa3b, v108
	v_mul_f32_e32 v109, 0xbfb8aa3b, v109
	v_exp_f32_e32 v106, v106
	v_exp_f32_e32 v107, v107
	v_exp_f32_e32 v108, v108
	v_exp_f32_e32 v109, v109
	v_add_f32_e32 v106, 1.0, v106
	v_add_f32_e32 v107, 1.0, v107
	v_add_f32_e32 v108, 1.0, v108
	v_add_f32_e32 v109, 1.0, v109
	v_rcp_f32_e32 v106, v106
	v_rcp_f32_e32 v107, v107
	v_rcp_f32_e32 v108, v108
	v_rcp_f32_e32 v109, v109
	v_mul_f32_e32 v110, 0xbfb8aa3b, v110
	v_mul_f32_e32 v111, 0xbfb8aa3b, v111
	v_mul_f32_e32 v112, 0xbfb8aa3b, v112
	v_mul_f32_e32 v113, 0xbfb8aa3b, v113
	v_exp_f32_e32 v110, v110
	v_exp_f32_e32 v111, v111
	v_exp_f32_e32 v112, v112
	v_exp_f32_e32 v113, v113
	v_add_f32_e32 v110, 1.0, v110
	v_add_f32_e32 v111, 1.0, v111
	v_add_f32_e32 v112, 1.0, v112
	v_add_f32_e32 v113, 1.0, v113
	v_rcp_f32_e32 v110, v110
	v_rcp_f32_e32 v111, v111
	v_rcp_f32_e32 v112, v112
	v_rcp_f32_e32 v113, v113
	v_mul_f32_e32 v114, 0xbfb8aa3b, v114
	v_mul_f32_e32 v115, 0xbfb8aa3b, v115
	v_mul_f32_e32 v116, 0xbfb8aa3b, v116
	v_mul_f32_e32 v117, 0xbfb8aa3b, v117
	v_exp_f32_e32 v114, v114
	v_exp_f32_e32 v115, v115
	v_exp_f32_e32 v116, v116
	v_exp_f32_e32 v117, v117
	v_add_f32_e32 v114, 1.0, v114
	v_add_f32_e32 v115, 1.0, v115
	v_add_f32_e32 v116, 1.0, v116
	v_add_f32_e32 v117, 1.0, v117
	v_rcp_f32_e32 v114, v114
	v_rcp_f32_e32 v115, v115
	v_rcp_f32_e32 v116, v116
	v_rcp_f32_e32 v117, v117
	v_mul_f32_e32 v118, 0xbfb8aa3b, v118
	v_mul_f32_e32 v119, 0xbfb8aa3b, v119
	v_mul_f32_e32 v120, 0xbfb8aa3b, v120
	v_mul_f32_e32 v121, 0xbfb8aa3b, v121
	v_exp_f32_e32 v118, v118
	v_exp_f32_e32 v119, v119
	v_exp_f32_e32 v120, v120
	v_exp_f32_e32 v121, v121
	v_add_f32_e32 v118, 1.0, v118
	v_add_f32_e32 v119, 1.0, v119
	v_add_f32_e32 v120, 1.0, v120
	v_add_f32_e32 v121, 1.0, v121
	v_rcp_f32_e32 v118, v118
	v_rcp_f32_e32 v119, v119
	v_rcp_f32_e32 v120, v120
	v_rcp_f32_e32 v121, v121
	v_mul_f32_e32 v122, 0xbfb8aa3b, v122
	v_mul_f32_e32 v123, 0xbfb8aa3b, v123
	v_mul_f32_e32 v124, 0xbfb8aa3b, v124
	v_mul_f32_e32 v125, 0xbfb8aa3b, v125
	v_exp_f32_e32 v122, v122
	v_exp_f32_e32 v123, v123
	v_exp_f32_e32 v124, v124
	v_exp_f32_e32 v125, v125
	v_add_f32_e32 v122, 1.0, v122
	v_add_f32_e32 v123, 1.0, v123
	v_add_f32_e32 v124, 1.0, v124
	v_add_f32_e32 v125, 1.0, v125
	v_rcp_f32_e32 v122, v122
	v_rcp_f32_e32 v123, v123
	v_rcp_f32_e32 v124, v124
	v_rcp_f32_e32 v125, v125
	v_mul_f32_e32 v126, 0xbfb8aa3b, v126
	v_mul_f32_e32 v127, 0xbfb8aa3b, v127
	v_mul_f32_e32 v128, 0xbfb8aa3b, v128
	v_mul_f32_e32 v129, 0xbfb8aa3b, v129
	v_exp_f32_e32 v126, v126
	v_exp_f32_e32 v127, v127
	v_exp_f32_e32 v128, v128
	v_exp_f32_e32 v129, v129
	v_add_f32_e32 v126, 1.0, v126
	v_add_f32_e32 v127, 1.0, v127
	v_add_f32_e32 v128, 1.0, v128
	v_add_f32_e32 v129, 1.0, v129
	v_rcp_f32_e32 v126, v126
	v_rcp_f32_e32 v127, v127
	v_rcp_f32_e32 v128, v128
	v_rcp_f32_e32 v129, v129
	s_waitcnt vmcnt(0)
	v_lshlrev_b32_e32 v194, 16, v228
	v_and_b32_e32 v195, 0xffff0000, v228
	v_lshlrev_b32_e32 v213, 16, v229
	v_and_b32_e32 v214, 0xffff0000, v229
	v_fma_f32 v2, v194, v66, v2
	v_fma_f32 v3, v195, v67, v3
	v_fma_f32 v4, v213, v68, v4
	v_fma_f32 v5, v214, v69, v5
	v_lshlrev_b32_e32 v194, 16, v230
	v_and_b32_e32 v195, 0xffff0000, v230
	v_lshlrev_b32_e32 v213, 16, v231
	v_and_b32_e32 v214, 0xffff0000, v231
	v_fma_f32 v6, v194, v70, v6
	v_fma_f32 v7, v195, v71, v7
	v_fma_f32 v8, v213, v72, v8
	v_fma_f32 v9, v214, v73, v9
	v_lshlrev_b32_e32 v194, 16, v232
	v_and_b32_e32 v195, 0xffff0000, v232
	v_lshlrev_b32_e32 v213, 16, v233
	v_and_b32_e32 v214, 0xffff0000, v233
	v_fma_f32 v10, v194, v74, v10
	v_fma_f32 v11, v195, v75, v11
	v_fma_f32 v12, v213, v76, v12
	v_fma_f32 v13, v214, v77, v13
	v_lshlrev_b32_e32 v194, 16, v234
	v_and_b32_e32 v195, 0xffff0000, v234
	v_lshlrev_b32_e32 v213, 16, v235
	v_and_b32_e32 v214, 0xffff0000, v235
	v_fma_f32 v14, v194, v78, v14
	v_fma_f32 v15, v195, v79, v15
	v_fma_f32 v16, v213, v80, v16
	v_fma_f32 v17, v214, v81, v17
	v_lshlrev_b32_e32 v194, 16, v236
	v_and_b32_e32 v195, 0xffff0000, v236
	v_lshlrev_b32_e32 v213, 16, v237
	v_and_b32_e32 v214, 0xffff0000, v237
	v_fma_f32 v18, v194, v82, v18
	v_fma_f32 v19, v195, v83, v19
	v_fma_f32 v20, v213, v84, v20
	v_fma_f32 v21, v214, v85, v21
	v_lshlrev_b32_e32 v194, 16, v238
	v_and_b32_e32 v195, 0xffff0000, v238
	v_lshlrev_b32_e32 v213, 16, v239
	v_and_b32_e32 v214, 0xffff0000, v239
	v_fma_f32 v22, v194, v86, v22
	v_fma_f32 v23, v195, v87, v23
	v_fma_f32 v24, v213, v88, v24
	v_fma_f32 v25, v214, v89, v25
	v_lshlrev_b32_e32 v194, 16, v240
	v_and_b32_e32 v195, 0xffff0000, v240
	v_lshlrev_b32_e32 v213, 16, v241
	v_and_b32_e32 v214, 0xffff0000, v241
	v_fma_f32 v26, v194, v90, v26
	v_fma_f32 v27, v195, v91, v27
	v_fma_f32 v28, v213, v92, v28
	v_fma_f32 v29, v214, v93, v29
	v_lshlrev_b32_e32 v194, 16, v242
	v_and_b32_e32 v195, 0xffff0000, v242
	v_lshlrev_b32_e32 v213, 16, v243
	v_and_b32_e32 v214, 0xffff0000, v243
	v_fma_f32 v30, v194, v94, v30
	v_fma_f32 v31, v195, v95, v31
	v_fma_f32 v32, v213, v96, v32
	v_fma_f32 v33, v214, v97, v33
	v_lshlrev_b32_e32 v194, 16, v244
	v_and_b32_e32 v195, 0xffff0000, v244
	v_lshlrev_b32_e32 v213, 16, v245
	v_and_b32_e32 v214, 0xffff0000, v245
	v_fma_f32 v34, v194, v98, v34
	v_fma_f32 v35, v195, v99, v35
	v_fma_f32 v36, v213, v100, v36
	v_fma_f32 v37, v214, v101, v37
	v_lshlrev_b32_e32 v194, 16, v246
	v_and_b32_e32 v195, 0xffff0000, v246
	v_lshlrev_b32_e32 v213, 16, v247
	v_and_b32_e32 v214, 0xffff0000, v247
	v_fma_f32 v38, v194, v102, v38
	v_fma_f32 v39, v195, v103, v39
	v_fma_f32 v40, v213, v104, v40
	v_fma_f32 v41, v214, v105, v41
	v_lshlrev_b32_e32 v194, 16, v248
	v_and_b32_e32 v195, 0xffff0000, v248
	v_lshlrev_b32_e32 v213, 16, v249
	v_and_b32_e32 v214, 0xffff0000, v249
	v_fma_f32 v42, v194, v106, v42
	v_fma_f32 v43, v195, v107, v43
	v_fma_f32 v44, v213, v108, v44
	v_fma_f32 v45, v214, v109, v45
	v_lshlrev_b32_e32 v194, 16, v250
	v_and_b32_e32 v195, 0xffff0000, v250
	v_lshlrev_b32_e32 v213, 16, v251
	v_and_b32_e32 v214, 0xffff0000, v251
	v_fma_f32 v46, v194, v110, v46
	v_fma_f32 v47, v195, v111, v47
	v_fma_f32 v48, v213, v112, v48
	v_fma_f32 v49, v214, v113, v49
	v_lshlrev_b32_e32 v194, 16, v252
	v_and_b32_e32 v195, 0xffff0000, v252
	v_lshlrev_b32_e32 v213, 16, v253
	v_and_b32_e32 v214, 0xffff0000, v253
	v_fma_f32 v50, v194, v114, v50
	v_fma_f32 v51, v195, v115, v51
	v_fma_f32 v52, v213, v116, v52
	v_fma_f32 v53, v214, v117, v53
	v_lshlrev_b32_e32 v194, 16, v254
	v_and_b32_e32 v195, 0xffff0000, v254
	v_lshlrev_b32_e32 v213, 16, v255
	v_and_b32_e32 v214, 0xffff0000, v255
	v_fma_f32 v54, v194, v118, v54
	v_fma_f32 v55, v195, v119, v55
	v_fma_f32 v56, v213, v120, v56
	v_fma_f32 v57, v214, v121, v57
	v_lshlrev_b32_e32 v194, 16, v216
	v_and_b32_e32 v195, 0xffff0000, v216
	v_lshlrev_b32_e32 v213, 16, v217
	v_and_b32_e32 v214, 0xffff0000, v217
	v_fma_f32 v58, v194, v122, v58
	v_fma_f32 v59, v195, v123, v59
	v_fma_f32 v60, v213, v124, v60
	v_fma_f32 v61, v214, v125, v61
	v_lshlrev_b32_e32 v194, 16, v218
	v_and_b32_e32 v195, 0xffff0000, v218
	v_lshlrev_b32_e32 v213, 16, v219
	v_and_b32_e32 v214, 0xffff0000, v219
	v_fma_f32 v62, v194, v126, v62
	v_fma_f32 v63, v195, v127, v63
	v_fma_f32 v64, v213, v128, v64
	v_fma_f32 v65, v214, v129, v65
	s_add_u32 s38, s42, 0x1a81c000
	s_addc_u32 s39, s43, 0
	s_add_u32 s38, s38, s2
	s_addc_u32 s39, s39, 0
	s_nop 0
	global_load_dwordx2 v[228:229], v215, s[38:39] offset:0
	global_load_dwordx2 v[230:231], v215, s[38:39] offset:32
	global_load_dwordx2 v[232:233], v215, s[38:39] offset:64
	global_load_dwordx2 v[234:235], v215, s[38:39] offset:96
	global_load_dwordx2 v[236:237], v220, s[38:39] offset:0
	global_load_dwordx2 v[238:239], v220, s[38:39] offset:32
	global_load_dwordx2 v[240:241], v220, s[38:39] offset:64
	global_load_dwordx2 v[242:243], v220, s[38:39] offset:96
	global_load_dwordx2 v[244:245], v227, s[38:39] offset:0
	global_load_dwordx2 v[246:247], v227, s[38:39] offset:32
	global_load_dwordx2 v[248:249], v227, s[38:39] offset:64
	global_load_dwordx2 v[250:251], v227, s[38:39] offset:96
	global_load_dwordx2 v[252:253], v0, s[38:39] offset:0
	global_load_dwordx2 v[254:255], v0, s[38:39] offset:32
	global_load_dwordx2 v[216:217], v0, s[38:39] offset:64
	global_load_dwordx2 v[218:219], v0, s[38:39] offset:96
	v_mul_f32_e32 v130, 0xbfb8aa3b, v130
	v_mul_f32_e32 v131, 0xbfb8aa3b, v131
	v_mul_f32_e32 v132, 0xbfb8aa3b, v132
	v_mul_f32_e32 v133, 0xbfb8aa3b, v133
	v_exp_f32_e32 v130, v130
	v_exp_f32_e32 v131, v131
	v_exp_f32_e32 v132, v132
	v_exp_f32_e32 v133, v133
	v_add_f32_e32 v130, 1.0, v130
	v_add_f32_e32 v131, 1.0, v131
	v_add_f32_e32 v132, 1.0, v132
	v_add_f32_e32 v133, 1.0, v133
	v_rcp_f32_e32 v130, v130
	v_rcp_f32_e32 v131, v131
	v_rcp_f32_e32 v132, v132
	v_rcp_f32_e32 v133, v133
	v_mul_f32_e32 v134, 0xbfb8aa3b, v134
	v_mul_f32_e32 v135, 0xbfb8aa3b, v135
	v_mul_f32_e32 v136, 0xbfb8aa3b, v136
	v_mul_f32_e32 v137, 0xbfb8aa3b, v137
	v_exp_f32_e32 v134, v134
	v_exp_f32_e32 v135, v135
	v_exp_f32_e32 v136, v136
	v_exp_f32_e32 v137, v137
	v_add_f32_e32 v134, 1.0, v134
	v_add_f32_e32 v135, 1.0, v135
	v_add_f32_e32 v136, 1.0, v136
	v_add_f32_e32 v137, 1.0, v137
	v_rcp_f32_e32 v134, v134
	v_rcp_f32_e32 v135, v135
	v_rcp_f32_e32 v136, v136
	v_rcp_f32_e32 v137, v137
	v_mul_f32_e32 v138, 0xbfb8aa3b, v138
	v_mul_f32_e32 v139, 0xbfb8aa3b, v139
	v_mul_f32_e32 v140, 0xbfb8aa3b, v140
	v_mul_f32_e32 v141, 0xbfb8aa3b, v141
	v_exp_f32_e32 v138, v138
	v_exp_f32_e32 v139, v139
	v_exp_f32_e32 v140, v140
	v_exp_f32_e32 v141, v141
	v_add_f32_e32 v138, 1.0, v138
	v_add_f32_e32 v139, 1.0, v139
	v_add_f32_e32 v140, 1.0, v140
	v_add_f32_e32 v141, 1.0, v141
	v_rcp_f32_e32 v138, v138
	v_rcp_f32_e32 v139, v139
	v_rcp_f32_e32 v140, v140
	v_rcp_f32_e32 v141, v141
	v_mul_f32_e32 v142, 0xbfb8aa3b, v142
	v_mul_f32_e32 v143, 0xbfb8aa3b, v143
	v_mul_f32_e32 v144, 0xbfb8aa3b, v144
	v_mul_f32_e32 v145, 0xbfb8aa3b, v145
	v_exp_f32_e32 v142, v142
	v_exp_f32_e32 v143, v143
	v_exp_f32_e32 v144, v144
	v_exp_f32_e32 v145, v145
	v_add_f32_e32 v142, 1.0, v142
	v_add_f32_e32 v143, 1.0, v143
	v_add_f32_e32 v144, 1.0, v144
	v_add_f32_e32 v145, 1.0, v145
	v_rcp_f32_e32 v142, v142
	v_rcp_f32_e32 v143, v143
	v_rcp_f32_e32 v144, v144
	v_rcp_f32_e32 v145, v145
	v_mul_f32_e32 v146, 0xbfb8aa3b, v146
	v_mul_f32_e32 v147, 0xbfb8aa3b, v147
	v_mul_f32_e32 v148, 0xbfb8aa3b, v148
	v_mul_f32_e32 v149, 0xbfb8aa3b, v149
	v_exp_f32_e32 v146, v146
	v_exp_f32_e32 v147, v147
	v_exp_f32_e32 v148, v148
	v_exp_f32_e32 v149, v149
	v_add_f32_e32 v146, 1.0, v146
	v_add_f32_e32 v147, 1.0, v147
	v_add_f32_e32 v148, 1.0, v148
	v_add_f32_e32 v149, 1.0, v149
	v_rcp_f32_e32 v146, v146
	v_rcp_f32_e32 v147, v147
	v_rcp_f32_e32 v148, v148
	v_rcp_f32_e32 v149, v149
	v_mul_f32_e32 v150, 0xbfb8aa3b, v150
	v_mul_f32_e32 v151, 0xbfb8aa3b, v151
	v_mul_f32_e32 v152, 0xbfb8aa3b, v152
	v_mul_f32_e32 v153, 0xbfb8aa3b, v153
	v_exp_f32_e32 v150, v150
	v_exp_f32_e32 v151, v151
	v_exp_f32_e32 v152, v152
	v_exp_f32_e32 v153, v153
	v_add_f32_e32 v150, 1.0, v150
	v_add_f32_e32 v151, 1.0, v151
	v_add_f32_e32 v152, 1.0, v152
	v_add_f32_e32 v153, 1.0, v153
	v_rcp_f32_e32 v150, v150
	v_rcp_f32_e32 v151, v151
	v_rcp_f32_e32 v152, v152
	v_rcp_f32_e32 v153, v153
	v_mul_f32_e32 v154, 0xbfb8aa3b, v154
	v_mul_f32_e32 v155, 0xbfb8aa3b, v155
	v_mul_f32_e32 v156, 0xbfb8aa3b, v156
	v_mul_f32_e32 v157, 0xbfb8aa3b, v157
	v_exp_f32_e32 v154, v154
	v_exp_f32_e32 v155, v155
	v_exp_f32_e32 v156, v156
	v_exp_f32_e32 v157, v157
	v_add_f32_e32 v154, 1.0, v154
	v_add_f32_e32 v155, 1.0, v155
	v_add_f32_e32 v156, 1.0, v156
	v_add_f32_e32 v157, 1.0, v157
	v_rcp_f32_e32 v154, v154
	v_rcp_f32_e32 v155, v155
	v_rcp_f32_e32 v156, v156
	v_rcp_f32_e32 v157, v157
	v_mul_f32_e32 v158, 0xbfb8aa3b, v158
	v_mul_f32_e32 v159, 0xbfb8aa3b, v159
	v_mul_f32_e32 v160, 0xbfb8aa3b, v160
	v_mul_f32_e32 v161, 0xbfb8aa3b, v161
	v_exp_f32_e32 v158, v158
	v_exp_f32_e32 v159, v159
	v_exp_f32_e32 v160, v160
	v_exp_f32_e32 v161, v161
	v_add_f32_e32 v158, 1.0, v158
	v_add_f32_e32 v159, 1.0, v159
	v_add_f32_e32 v160, 1.0, v160
	v_add_f32_e32 v161, 1.0, v161
	v_rcp_f32_e32 v158, v158
	v_rcp_f32_e32 v159, v159
	v_rcp_f32_e32 v160, v160
	v_rcp_f32_e32 v161, v161
	v_mul_f32_e32 v162, 0xbfb8aa3b, v162
	v_mul_f32_e32 v163, 0xbfb8aa3b, v163
	v_mul_f32_e32 v164, 0xbfb8aa3b, v164
	v_mul_f32_e32 v165, 0xbfb8aa3b, v165
	v_exp_f32_e32 v162, v162
	v_exp_f32_e32 v163, v163
	v_exp_f32_e32 v164, v164
	v_exp_f32_e32 v165, v165
	v_add_f32_e32 v162, 1.0, v162
	v_add_f32_e32 v163, 1.0, v163
	v_add_f32_e32 v164, 1.0, v164
	v_add_f32_e32 v165, 1.0, v165
	v_rcp_f32_e32 v162, v162
	v_rcp_f32_e32 v163, v163
	v_rcp_f32_e32 v164, v164
	v_rcp_f32_e32 v165, v165
	v_mul_f32_e32 v166, 0xbfb8aa3b, v166
	v_mul_f32_e32 v167, 0xbfb8aa3b, v167
	v_mul_f32_e32 v168, 0xbfb8aa3b, v168
	v_mul_f32_e32 v169, 0xbfb8aa3b, v169
	v_exp_f32_e32 v166, v166
	v_exp_f32_e32 v167, v167
	v_exp_f32_e32 v168, v168
	v_exp_f32_e32 v169, v169
	v_add_f32_e32 v166, 1.0, v166
	v_add_f32_e32 v167, 1.0, v167
	v_add_f32_e32 v168, 1.0, v168
	v_add_f32_e32 v169, 1.0, v169
	v_rcp_f32_e32 v166, v166
	v_rcp_f32_e32 v167, v167
	v_rcp_f32_e32 v168, v168
	v_rcp_f32_e32 v169, v169
	v_mul_f32_e32 v170, 0xbfb8aa3b, v170
	v_mul_f32_e32 v171, 0xbfb8aa3b, v171
	v_mul_f32_e32 v172, 0xbfb8aa3b, v172
	v_mul_f32_e32 v173, 0xbfb8aa3b, v173
	v_exp_f32_e32 v170, v170
	v_exp_f32_e32 v171, v171
	v_exp_f32_e32 v172, v172
	v_exp_f32_e32 v173, v173
	v_add_f32_e32 v170, 1.0, v170
	v_add_f32_e32 v171, 1.0, v171
	v_add_f32_e32 v172, 1.0, v172
	v_add_f32_e32 v173, 1.0, v173
	v_rcp_f32_e32 v170, v170
	v_rcp_f32_e32 v171, v171
	v_rcp_f32_e32 v172, v172
	v_rcp_f32_e32 v173, v173
	v_mul_f32_e32 v174, 0xbfb8aa3b, v174
	v_mul_f32_e32 v175, 0xbfb8aa3b, v175
	v_mul_f32_e32 v176, 0xbfb8aa3b, v176
	v_mul_f32_e32 v177, 0xbfb8aa3b, v177
	v_exp_f32_e32 v174, v174
	v_exp_f32_e32 v175, v175
	v_exp_f32_e32 v176, v176
	v_exp_f32_e32 v177, v177
	v_add_f32_e32 v174, 1.0, v174
	v_add_f32_e32 v175, 1.0, v175
	v_add_f32_e32 v176, 1.0, v176
	v_add_f32_e32 v177, 1.0, v177
	v_rcp_f32_e32 v174, v174
	v_rcp_f32_e32 v175, v175
	v_rcp_f32_e32 v176, v176
	v_rcp_f32_e32 v177, v177
	v_mul_f32_e32 v178, 0xbfb8aa3b, v178
	v_mul_f32_e32 v179, 0xbfb8aa3b, v179
	v_mul_f32_e32 v180, 0xbfb8aa3b, v180
	v_mul_f32_e32 v181, 0xbfb8aa3b, v181
	v_exp_f32_e32 v178, v178
	v_exp_f32_e32 v179, v179
	v_exp_f32_e32 v180, v180
	v_exp_f32_e32 v181, v181
	v_add_f32_e32 v178, 1.0, v178
	v_add_f32_e32 v179, 1.0, v179
	v_add_f32_e32 v180, 1.0, v180
	v_add_f32_e32 v181, 1.0, v181
	v_rcp_f32_e32 v178, v178
	v_rcp_f32_e32 v179, v179
	v_rcp_f32_e32 v180, v180
	v_rcp_f32_e32 v181, v181
	v_mul_f32_e32 v182, 0xbfb8aa3b, v182
	v_mul_f32_e32 v183, 0xbfb8aa3b, v183
	v_mul_f32_e32 v184, 0xbfb8aa3b, v184
	v_mul_f32_e32 v185, 0xbfb8aa3b, v185
	v_exp_f32_e32 v182, v182
	v_exp_f32_e32 v183, v183
	v_exp_f32_e32 v184, v184
	v_exp_f32_e32 v185, v185
	v_add_f32_e32 v182, 1.0, v182
	v_add_f32_e32 v183, 1.0, v183
	v_add_f32_e32 v184, 1.0, v184
	v_add_f32_e32 v185, 1.0, v185
	v_rcp_f32_e32 v182, v182
	v_rcp_f32_e32 v183, v183
	v_rcp_f32_e32 v184, v184
	v_rcp_f32_e32 v185, v185
	v_mul_f32_e32 v186, 0xbfb8aa3b, v186
	v_mul_f32_e32 v187, 0xbfb8aa3b, v187
	v_mul_f32_e32 v188, 0xbfb8aa3b, v188
	v_mul_f32_e32 v189, 0xbfb8aa3b, v189
	v_exp_f32_e32 v186, v186
	v_exp_f32_e32 v187, v187
	v_exp_f32_e32 v188, v188
	v_exp_f32_e32 v189, v189
	v_add_f32_e32 v186, 1.0, v186
	v_add_f32_e32 v187, 1.0, v187
	v_add_f32_e32 v188, 1.0, v188
	v_add_f32_e32 v189, 1.0, v189
	v_rcp_f32_e32 v186, v186
	v_rcp_f32_e32 v187, v187
	v_rcp_f32_e32 v188, v188
	v_rcp_f32_e32 v189, v189
	v_mul_f32_e32 v190, 0xbfb8aa3b, v190
	v_mul_f32_e32 v191, 0xbfb8aa3b, v191
	v_mul_f32_e32 v192, 0xbfb8aa3b, v192
	v_mul_f32_e32 v193, 0xbfb8aa3b, v193
	v_exp_f32_e32 v190, v190
	v_exp_f32_e32 v191, v191
	v_exp_f32_e32 v192, v192
	v_exp_f32_e32 v193, v193
	v_add_f32_e32 v190, 1.0, v190
	v_add_f32_e32 v191, 1.0, v191
	v_add_f32_e32 v192, 1.0, v192
	v_add_f32_e32 v193, 1.0, v193
	v_rcp_f32_e32 v190, v190
	v_rcp_f32_e32 v191, v191
	v_rcp_f32_e32 v192, v192
	v_rcp_f32_e32 v193, v193
	s_waitcnt vmcnt(0)
	v_lshlrev_b32_e32 v194, 16, v228
	v_and_b32_e32 v195, 0xffff0000, v228
	v_lshlrev_b32_e32 v213, 16, v229
	v_and_b32_e32 v214, 0xffff0000, v229
	v_fma_f32 v2, v194, v130, v2
	v_fma_f32 v3, v195, v131, v3
	v_fma_f32 v4, v213, v132, v4
	v_fma_f32 v5, v214, v133, v5
	v_lshlrev_b32_e32 v194, 16, v230
	v_and_b32_e32 v195, 0xffff0000, v230
	v_lshlrev_b32_e32 v213, 16, v231
	v_and_b32_e32 v214, 0xffff0000, v231
	v_fma_f32 v6, v194, v134, v6
	v_fma_f32 v7, v195, v135, v7
	v_fma_f32 v8, v213, v136, v8
	v_fma_f32 v9, v214, v137, v9
	v_lshlrev_b32_e32 v194, 16, v232
	v_and_b32_e32 v195, 0xffff0000, v232
	v_lshlrev_b32_e32 v213, 16, v233
	v_and_b32_e32 v214, 0xffff0000, v233
	v_fma_f32 v10, v194, v138, v10
	v_fma_f32 v11, v195, v139, v11
	v_fma_f32 v12, v213, v140, v12
	v_fma_f32 v13, v214, v141, v13
	v_lshlrev_b32_e32 v194, 16, v234
	v_and_b32_e32 v195, 0xffff0000, v234
	v_lshlrev_b32_e32 v213, 16, v235
	v_and_b32_e32 v214, 0xffff0000, v235
	v_fma_f32 v14, v194, v142, v14
	v_fma_f32 v15, v195, v143, v15
	v_fma_f32 v16, v213, v144, v16
	v_fma_f32 v17, v214, v145, v17
	v_lshlrev_b32_e32 v194, 16, v236
	v_and_b32_e32 v195, 0xffff0000, v236
	v_lshlrev_b32_e32 v213, 16, v237
	v_and_b32_e32 v214, 0xffff0000, v237
	v_fma_f32 v18, v194, v146, v18
	v_fma_f32 v19, v195, v147, v19
	v_fma_f32 v20, v213, v148, v20
	v_fma_f32 v21, v214, v149, v21
	v_lshlrev_b32_e32 v194, 16, v238
	v_and_b32_e32 v195, 0xffff0000, v238
	v_lshlrev_b32_e32 v213, 16, v239
	v_and_b32_e32 v214, 0xffff0000, v239
	v_fma_f32 v22, v194, v150, v22
	v_fma_f32 v23, v195, v151, v23
	v_fma_f32 v24, v213, v152, v24
	v_fma_f32 v25, v214, v153, v25
	v_lshlrev_b32_e32 v194, 16, v240
	v_and_b32_e32 v195, 0xffff0000, v240
	v_lshlrev_b32_e32 v213, 16, v241
	v_and_b32_e32 v214, 0xffff0000, v241
	v_fma_f32 v26, v194, v154, v26
	v_fma_f32 v27, v195, v155, v27
	v_fma_f32 v28, v213, v156, v28
	v_fma_f32 v29, v214, v157, v29
	v_lshlrev_b32_e32 v194, 16, v242
	v_and_b32_e32 v195, 0xffff0000, v242
	v_lshlrev_b32_e32 v213, 16, v243
	v_and_b32_e32 v214, 0xffff0000, v243
	v_fma_f32 v30, v194, v158, v30
	v_fma_f32 v31, v195, v159, v31
	v_fma_f32 v32, v213, v160, v32
	v_fma_f32 v33, v214, v161, v33
	v_lshlrev_b32_e32 v194, 16, v244
	v_and_b32_e32 v195, 0xffff0000, v244
	v_lshlrev_b32_e32 v213, 16, v245
	v_and_b32_e32 v214, 0xffff0000, v245
	v_fma_f32 v34, v194, v162, v34
	v_fma_f32 v35, v195, v163, v35
	v_fma_f32 v36, v213, v164, v36
	v_fma_f32 v37, v214, v165, v37
	v_lshlrev_b32_e32 v194, 16, v246
	v_and_b32_e32 v195, 0xffff0000, v246
	v_lshlrev_b32_e32 v213, 16, v247
	v_and_b32_e32 v214, 0xffff0000, v247
	v_fma_f32 v38, v194, v166, v38
	v_fma_f32 v39, v195, v167, v39
	v_fma_f32 v40, v213, v168, v40
	v_fma_f32 v41, v214, v169, v41
	v_lshlrev_b32_e32 v194, 16, v248
	v_and_b32_e32 v195, 0xffff0000, v248
	v_lshlrev_b32_e32 v213, 16, v249
	v_and_b32_e32 v214, 0xffff0000, v249
	v_fma_f32 v42, v194, v170, v42
	v_fma_f32 v43, v195, v171, v43
	v_fma_f32 v44, v213, v172, v44
	v_fma_f32 v45, v214, v173, v45
	v_lshlrev_b32_e32 v194, 16, v250
	v_and_b32_e32 v195, 0xffff0000, v250
	v_lshlrev_b32_e32 v213, 16, v251
	v_and_b32_e32 v214, 0xffff0000, v251
	v_fma_f32 v46, v194, v174, v46
	v_fma_f32 v47, v195, v175, v47
	v_fma_f32 v48, v213, v176, v48
	v_fma_f32 v49, v214, v177, v49
	v_lshlrev_b32_e32 v194, 16, v252
	v_and_b32_e32 v195, 0xffff0000, v252
	v_lshlrev_b32_e32 v213, 16, v253
	v_and_b32_e32 v214, 0xffff0000, v253
	v_fma_f32 v50, v194, v178, v50
	v_fma_f32 v51, v195, v179, v51
	v_fma_f32 v52, v213, v180, v52
	v_fma_f32 v53, v214, v181, v53
	v_lshlrev_b32_e32 v194, 16, v254
	v_and_b32_e32 v195, 0xffff0000, v254
	v_lshlrev_b32_e32 v213, 16, v255
	v_and_b32_e32 v214, 0xffff0000, v255
	v_fma_f32 v54, v194, v182, v54
	v_fma_f32 v55, v195, v183, v55
	v_fma_f32 v56, v213, v184, v56
	v_fma_f32 v57, v214, v185, v57
	v_lshlrev_b32_e32 v194, 16, v216
	v_and_b32_e32 v195, 0xffff0000, v216
	v_lshlrev_b32_e32 v213, 16, v217
	v_and_b32_e32 v214, 0xffff0000, v217
	v_fma_f32 v58, v194, v186, v58
	v_fma_f32 v59, v195, v187, v59
	v_fma_f32 v60, v213, v188, v60
	v_fma_f32 v61, v214, v189, v61
	v_lshlrev_b32_e32 v194, 16, v218
	v_and_b32_e32 v195, 0xffff0000, v218
	v_lshlrev_b32_e32 v213, 16, v219
	v_and_b32_e32 v214, 0xffff0000, v219
	v_fma_f32 v62, v194, v190, v62
	v_fma_f32 v63, v195, v191, v63
	v_fma_f32 v64, v213, v192, v64
	v_fma_f32 v65, v214, v193, v65
	v_and_b32_e32 v213, 15, v196
	v_lshrrev_b32_e32 v220, 7, v196
	v_lshl_add_u32 v213, v220, 6, v213
	v_mul_u32_u24_e32 v213, 0x110, v213
	v_bfe_u32 v220, v196, 6, 1
	v_lshl_add_u32 v213, v220, 7, v213
	v_bfe_u32 v220, v196, 4, 2
	v_lshl_add_u32 v213, v220, 3, v213
	v_cvt_pk_bf16_f32 v194, v2, v3
	v_cvt_pk_bf16_f32 v195, v4, v5
	ds_write_b64 v213, v[194:195] offset:0
	v_cvt_pk_bf16_f32 v214, v6, v7
	v_cvt_pk_bf16_f32 v215, v8, v9
	ds_write_b64 v213, v[214:215] offset:32
	v_cvt_pk_bf16_f32 v194, v10, v11
	v_cvt_pk_bf16_f32 v195, v12, v13
	ds_write_b64 v213, v[194:195] offset:64
	v_cvt_pk_bf16_f32 v214, v14, v15
	v_cvt_pk_bf16_f32 v215, v16, v17
	ds_write_b64 v213, v[214:215] offset:96
	v_cvt_pk_bf16_f32 v194, v18, v19
	v_cvt_pk_bf16_f32 v195, v20, v21
	ds_write_b64 v213, v[194:195] offset:4352
	v_cvt_pk_bf16_f32 v214, v22, v23
	v_cvt_pk_bf16_f32 v215, v24, v25
	ds_write_b64 v213, v[214:215] offset:4384
	v_cvt_pk_bf16_f32 v194, v26, v27
	v_cvt_pk_bf16_f32 v195, v28, v29
	ds_write_b64 v213, v[194:195] offset:4416
	v_cvt_pk_bf16_f32 v214, v30, v31
	v_cvt_pk_bf16_f32 v215, v32, v33
	ds_write_b64 v213, v[214:215] offset:4448
	v_cvt_pk_bf16_f32 v194, v34, v35
	v_cvt_pk_bf16_f32 v195, v36, v37
	ds_write_b64 v213, v[194:195] offset:8704
	v_cvt_pk_bf16_f32 v214, v38, v39
	v_cvt_pk_bf16_f32 v215, v40, v41
	ds_write_b64 v213, v[214:215] offset:8736
	v_cvt_pk_bf16_f32 v194, v42, v43
	v_cvt_pk_bf16_f32 v195, v44, v45
	ds_write_b64 v213, v[194:195] offset:8768
	v_cvt_pk_bf16_f32 v214, v46, v47
	v_cvt_pk_bf16_f32 v215, v48, v49
	ds_write_b64 v213, v[214:215] offset:8800
	v_cvt_pk_bf16_f32 v194, v50, v51
	v_cvt_pk_bf16_f32 v195, v52, v53
	ds_write_b64 v213, v[194:195] offset:13056
	v_cvt_pk_bf16_f32 v214, v54, v55
	v_cvt_pk_bf16_f32 v215, v56, v57
	ds_write_b64 v213, v[214:215] offset:13088
	v_cvt_pk_bf16_f32 v194, v58, v59
	v_cvt_pk_bf16_f32 v195, v60, v61
	ds_write_b64 v213, v[194:195] offset:13120
	v_cvt_pk_bf16_f32 v214, v62, v63
	v_cvt_pk_bf16_f32 v215, v64, v65
	ds_write_b64 v213, v[214:215] offset:13152
	v_lshrrev_b32_e32 v220, 4, v196
	v_and_b32_e32 v0, 15, v196
	v_lshlrev_b32_e32 v0, 4, v0
	v_lshl_add_u32 v227, v220, 11, v0
	v_mad_u32_u24 v220, v220, s30, v0
	s_add_u32 s38, s19, s2
	s_addc_u32 s39, s20, 0
	s_waitcnt lgkmcnt(0)
	s_barrier
	ds_read_b128 v[228:231], v220 offset:0
	ds_read_b128 v[232:235], v220 offset:4352
	ds_read_b128 v[236:239], v220 offset:8704
	ds_read_b128 v[240:243], v220 offset:13056
	ds_read_b128 v[244:247], v220 offset:17408
	ds_read_b128 v[248:251], v220 offset:21760
	ds_read_b128 v[252:255], v220 offset:26112
	ds_read_b128 v[216:219], v220 offset:30464
	s_waitcnt lgkmcnt(7)
	global_store_dwordx4 v227, v[228:231], s[38:39]
	v_add_u32_e32 v227, 0x8000, v227
	s_waitcnt lgkmcnt(6)
	global_store_dwordx4 v227, v[232:235], s[38:39]
	v_add_u32_e32 v227, 0x8000, v227
	s_waitcnt lgkmcnt(5)
	global_store_dwordx4 v227, v[236:239], s[38:39]
	v_add_u32_e32 v227, 0x8000, v227
	s_waitcnt lgkmcnt(4)
	global_store_dwordx4 v227, v[240:243], s[38:39]
	v_add_u32_e32 v227, 0x8000, v227
	s_waitcnt lgkmcnt(3)
	global_store_dwordx4 v227, v[244:247], s[38:39]
	v_add_u32_e32 v227, 0x8000, v227
	s_waitcnt lgkmcnt(2)
	global_store_dwordx4 v227, v[248:251], s[38:39]
	v_add_u32_e32 v227, 0x8000, v227
	s_waitcnt lgkmcnt(1)
	global_store_dwordx4 v227, v[252:255], s[38:39]
	v_add_u32_e32 v227, 0x8000, v227
	s_waitcnt lgkmcnt(0)
	global_store_dwordx4 v227, v[216:219], s[38:39]
	s_barrier
	v_readlane_b32 s0, v225, 42
	v_readlane_b32 s1, v225, 43
	s_load_dword s0, s[0:1], 0x0
	s_waitcnt lgkmcnt(0)
	s_add_i32 s24, s0, s24
	s_cmp_ge_i32 s24, s14
	s_cbranch_scc0 .LBB0_189
